# rope dword copy loop unrolled x7 with all loads in flight before the stores (one round trip instead of seven)
# speedup vs baseline: 1.0059x; 1.0044x over previous
; __device__ __forceinline__ void prep_rope(Frame& F, const Args& a, int idx, int nwg) {
;     ...
;         for (int e = F.tid; e < TT * 224; e += NTHR) {
;             const int tt = e / 224, r = e % 224, gg = r / 112, c2 = r % 112, t = t0 + tt;
;             unsigned* dst = (unsigned*)((bf16_t*)(F.ws + WS_KV2) + ((size_t)t * 2 + gg) * 256);
;             if (c2 < 48) dst[16 + c2] = ((const unsigned*)(U + (size_t)t * PWP + UK + 128 * gg + 32))[c2];
;             else dst[64 + (c2 - 48)] = ((const unsigned*)(U + (size_t)t * PWP + UV + 128 * gg))[c2 - 48];
;         }
.LBB0_776:
	v_lshrrev_b32_e32 v0, 5, v6
	v_mul_hi_u32 v0, v0, s51
	v_mov_b64_e32 v[8:9], s[34:35]
	v_add_u32_e32 v20, s57, v0
	v_mad_u64_u32 v[10:11], s[6:7], v0, s52, v[6:7]
	v_mad_i64_i32 v[8:9], s[6:7], v20, s28, v[8:9]
	v_add_u16_e32 v7, 0xff90, v10
	v_ashrrev_i32_e32 v21, 31, v20
	v_cmp_gt_u32_e64 s[6:7], s54, v10
	v_cmp_lt_u32_e32 vcc, s53, v10
	s_nop 0
	v_cndmask_b32_e64 v7, v7, v10, s[6:7]
	v_lshlrev_b64 v[10:11], 10, v[20:21]
	v_cndmask_b32_e32 v0, 0, v16, vcc
	v_lshl_add_u64 v[10:11], s[24:25], 0, v[10:11]
	v_lshl_add_u64 v[10:11], v[10:11], 0, v[0:1]
	v_cndmask_b32_e32 v0, 0, v17, vcc
	v_lshl_add_u64 v[8:9], v[8:9], 0, v[0:1]
	v_lshlrev_b32_sdwa v0, v18, v7 dst_sel:DWORD dst_unused:UNUSED_PAD src0_sel:DWORD src1_sel:WORD_0
	v_lshl_add_u64 v[8:9], v[8:9], 0, v[0:1]
	v_lshl_add_u64 v[20:21], v[8:9], 0, s[12:13]
	v_lshl_add_u64 v[8:9], v[8:9], 0, s[14:15]
	v_cmp_gt_u16_e32 vcc, 48, v7
	s_nop 1
	v_cndmask_b32_e32 v9, v21, v9, vcc
	v_cndmask_b32_e32 v8, v20, v8, vcc
	global_load_dword v96, v[8:9], off
	v_lshl_add_u64 v[104:105], v[10:11], 0, v[0:1]
	v_add_u32_e32 v6, 0x200, v6
	v_lshrrev_b32_e32 v0, 5, v6
	v_mul_hi_u32 v0, v0, s51
	v_mov_b64_e32 v[8:9], s[34:35]
	v_add_u32_e32 v20, s57, v0
	v_mad_u64_u32 v[10:11], s[6:7], v0, s52, v[6:7]
	v_mad_i64_i32 v[8:9], s[6:7], v20, s28, v[8:9]
	v_add_u16_e32 v7, 0xff90, v10
	v_ashrrev_i32_e32 v21, 31, v20
	v_cmp_gt_u32_e64 s[6:7], s54, v10
	v_cmp_lt_u32_e32 vcc, s53, v10
	s_nop 0
	v_cndmask_b32_e64 v7, v7, v10, s[6:7]
	v_lshlrev_b64 v[10:11], 10, v[20:21]
	v_cndmask_b32_e32 v0, 0, v16, vcc
	v_lshl_add_u64 v[10:11], s[24:25], 0, v[10:11]
	v_lshl_add_u64 v[10:11], v[10:11], 0, v[0:1]
	v_cndmask_b32_e32 v0, 0, v17, vcc
	v_lshl_add_u64 v[8:9], v[8:9], 0, v[0:1]
	v_lshlrev_b32_sdwa v0, v18, v7 dst_sel:DWORD dst_unused:UNUSED_PAD src0_sel:DWORD src1_sel:WORD_0
	v_lshl_add_u64 v[8:9], v[8:9], 0, v[0:1]
	v_lshl_add_u64 v[20:21], v[8:9], 0, s[12:13]
	v_lshl_add_u64 v[8:9], v[8:9], 0, s[14:15]
	v_cmp_gt_u16_e32 vcc, 48, v7
	s_nop 1
	v_cndmask_b32_e32 v9, v21, v9, vcc
	v_cndmask_b32_e32 v8, v20, v8, vcc
	global_load_dword v97, v[8:9], off
	v_lshl_add_u64 v[106:107], v[10:11], 0, v[0:1]
	v_add_u32_e32 v6, 0x200, v6
	v_lshrrev_b32_e32 v0, 5, v6
	v_mul_hi_u32 v0, v0, s51
	v_mov_b64_e32 v[8:9], s[34:35]
	v_add_u32_e32 v20, s57, v0
	v_mad_u64_u32 v[10:11], s[6:7], v0, s52, v[6:7]
	v_mad_i64_i32 v[8:9], s[6:7], v20, s28, v[8:9]
	v_add_u16_e32 v7, 0xff90, v10
	v_ashrrev_i32_e32 v21, 31, v20
	v_cmp_gt_u32_e64 s[6:7], s54, v10
	v_cmp_lt_u32_e32 vcc, s53, v10
	s_nop 0
	v_cndmask_b32_e64 v7, v7, v10, s[6:7]
	v_lshlrev_b64 v[10:11], 10, v[20:21]
	v_cndmask_b32_e32 v0, 0, v16, vcc
	v_lshl_add_u64 v[10:11], s[24:25], 0, v[10:11]
	v_lshl_add_u64 v[10:11], v[10:11], 0, v[0:1]
	v_cndmask_b32_e32 v0, 0, v17, vcc
	v_lshl_add_u64 v[8:9], v[8:9], 0, v[0:1]
	v_lshlrev_b32_sdwa v0, v18, v7 dst_sel:DWORD dst_unused:UNUSED_PAD src0_sel:DWORD src1_sel:WORD_0
	v_lshl_add_u64 v[8:9], v[8:9], 0, v[0:1]
	v_lshl_add_u64 v[20:21], v[8:9], 0, s[12:13]
	v_lshl_add_u64 v[8:9], v[8:9], 0, s[14:15]
	v_cmp_gt_u16_e32 vcc, 48, v7
	s_nop 1
	v_cndmask_b32_e32 v9, v21, v9, vcc
	v_cndmask_b32_e32 v8, v20, v8, vcc
	global_load_dword v98, v[8:9], off
	v_lshl_add_u64 v[108:109], v[10:11], 0, v[0:1]
	v_add_u32_e32 v6, 0x200, v6
	v_lshrrev_b32_e32 v0, 5, v6
	v_mul_hi_u32 v0, v0, s51
	v_mov_b64_e32 v[8:9], s[34:35]
	v_add_u32_e32 v20, s57, v0
	v_mad_u64_u32 v[10:11], s[6:7], v0, s52, v[6:7]
	v_mad_i64_i32 v[8:9], s[6:7], v20, s28, v[8:9]
	v_add_u16_e32 v7, 0xff90, v10
	v_ashrrev_i32_e32 v21, 31, v20
	v_cmp_gt_u32_e64 s[6:7], s54, v10
	v_cmp_lt_u32_e32 vcc, s53, v10
	s_nop 0
	v_cndmask_b32_e64 v7, v7, v10, s[6:7]
	v_lshlrev_b64 v[10:11], 10, v[20:21]
	v_cndmask_b32_e32 v0, 0, v16, vcc
	v_lshl_add_u64 v[10:11], s[24:25], 0, v[10:11]
	v_lshl_add_u64 v[10:11], v[10:11], 0, v[0:1]
	v_cndmask_b32_e32 v0, 0, v17, vcc
	v_lshl_add_u64 v[8:9], v[8:9], 0, v[0:1]
	v_lshlrev_b32_sdwa v0, v18, v7 dst_sel:DWORD dst_unused:UNUSED_PAD src0_sel:DWORD src1_sel:WORD_0
	v_lshl_add_u64 v[8:9], v[8:9], 0, v[0:1]
	v_lshl_add_u64 v[20:21], v[8:9], 0, s[12:13]
	v_lshl_add_u64 v[8:9], v[8:9], 0, s[14:15]
	v_cmp_gt_u16_e32 vcc, 48, v7
	s_nop 1
	v_cndmask_b32_e32 v9, v21, v9, vcc
	v_cndmask_b32_e32 v8, v20, v8, vcc
	global_load_dword v99, v[8:9], off
	v_lshl_add_u64 v[110:111], v[10:11], 0, v[0:1]
	v_add_u32_e32 v6, 0x200, v6
; __device__ __forceinline__ void prep_rope(Frame& F, const Args& a, int idx, int nwg) {
;     ...
;         for (int e = F.tid; e < TT * 224; e += NTHR) {
;             const int tt = e / 224, r = e % 224, gg = r / 112, c2 = r % 112, t = t0 + tt;
;             unsigned* dst = (unsigned*)((bf16_t*)(F.ws + WS_KV2) + ((size_t)t * 2 + gg) * 256);
;             if (c2 < 48) dst[16 + c2] = ((const unsigned*)(U + (size_t)t * PWP + UK + 128 * gg + 32))[c2];
;             else dst[64 + (c2 - 48)] = ((const unsigned*)(U + (size_t)t * PWP + UV + 128 * gg))[c2 - 48];
;         }
;         for (int e = F.tid; e < TT * 24; e += NTHR) {
;             const int tt = e / 24, c2 = e % 24, t = t0 + tt;
;             ((unsigned*)((bf16_t*)(F.ws + WS_KI2) + (size_t)t * 64 + 16))[c2] = ((const unsigned*)(U + (size_t)t * PWP + UKI + 16))[c2];
	v_lshrrev_b32_e32 v0, 5, v6
	v_mul_hi_u32 v0, v0, s51
	v_mov_b64_e32 v[8:9], s[34:35]
	v_add_u32_e32 v20, s57, v0
	v_mad_u64_u32 v[10:11], s[6:7], v0, s52, v[6:7]
	v_mad_i64_i32 v[8:9], s[6:7], v20, s28, v[8:9]
	v_add_u16_e32 v7, 0xff90, v10
	v_ashrrev_i32_e32 v21, 31, v20
	v_cmp_gt_u32_e64 s[6:7], s54, v10
	v_cmp_lt_u32_e32 vcc, s53, v10
	s_nop 0
	v_cndmask_b32_e64 v7, v7, v10, s[6:7]
	v_lshlrev_b64 v[10:11], 10, v[20:21]
	v_cndmask_b32_e32 v0, 0, v16, vcc
	v_lshl_add_u64 v[10:11], s[24:25], 0, v[10:11]
	v_lshl_add_u64 v[10:11], v[10:11], 0, v[0:1]
	v_cndmask_b32_e32 v0, 0, v17, vcc
	v_lshl_add_u64 v[8:9], v[8:9], 0, v[0:1]
	v_lshlrev_b32_sdwa v0, v18, v7 dst_sel:DWORD dst_unused:UNUSED_PAD src0_sel:DWORD src1_sel:WORD_0
	v_lshl_add_u64 v[8:9], v[8:9], 0, v[0:1]
	v_lshl_add_u64 v[20:21], v[8:9], 0, s[12:13]
	v_lshl_add_u64 v[8:9], v[8:9], 0, s[14:15]
	v_cmp_gt_u16_e32 vcc, 48, v7
	s_nop 1
	v_cndmask_b32_e32 v9, v21, v9, vcc
	v_cndmask_b32_e32 v8, v20, v8, vcc
	global_load_dword v100, v[8:9], off
	v_lshl_add_u64 v[112:113], v[10:11], 0, v[0:1]
	v_add_u32_e32 v6, 0x200, v6
	v_lshrrev_b32_e32 v0, 5, v6
	v_mul_hi_u32 v0, v0, s51
	v_mov_b64_e32 v[8:9], s[34:35]
	v_add_u32_e32 v20, s57, v0
	v_mad_u64_u32 v[10:11], s[6:7], v0, s52, v[6:7]
	v_mad_i64_i32 v[8:9], s[6:7], v20, s28, v[8:9]
	v_add_u16_e32 v7, 0xff90, v10
	v_ashrrev_i32_e32 v21, 31, v20
	v_cmp_gt_u32_e64 s[6:7], s54, v10
	v_cmp_lt_u32_e32 vcc, s53, v10
	s_nop 0
	v_cndmask_b32_e64 v7, v7, v10, s[6:7]
	v_lshlrev_b64 v[10:11], 10, v[20:21]
	v_cndmask_b32_e32 v0, 0, v16, vcc
	v_lshl_add_u64 v[10:11], s[24:25], 0, v[10:11]
	v_lshl_add_u64 v[10:11], v[10:11], 0, v[0:1]
	v_cndmask_b32_e32 v0, 0, v17, vcc
	v_lshl_add_u64 v[8:9], v[8:9], 0, v[0:1]
	v_lshlrev_b32_sdwa v0, v18, v7 dst_sel:DWORD dst_unused:UNUSED_PAD src0_sel:DWORD src1_sel:WORD_0
	v_lshl_add_u64 v[8:9], v[8:9], 0, v[0:1]
	v_lshl_add_u64 v[20:21], v[8:9], 0, s[12:13]
	v_lshl_add_u64 v[8:9], v[8:9], 0, s[14:15]
	v_cmp_gt_u16_e32 vcc, 48, v7
	s_nop 1
	v_cndmask_b32_e32 v9, v21, v9, vcc
	v_cndmask_b32_e32 v8, v20, v8, vcc
	global_load_dword v101, v[8:9], off
	v_lshl_add_u64 v[114:115], v[10:11], 0, v[0:1]
	v_add_u32_e32 v6, 0x200, v6
	v_lshrrev_b32_e32 v0, 5, v6
	v_mul_hi_u32 v0, v0, s51
	v_mov_b64_e32 v[8:9], s[34:35]
	v_add_u32_e32 v20, s57, v0
	v_mad_u64_u32 v[10:11], s[6:7], v0, s52, v[6:7]
	v_mad_i64_i32 v[8:9], s[6:7], v20, s28, v[8:9]
	v_add_u16_e32 v7, 0xff90, v10
	v_ashrrev_i32_e32 v21, 31, v20
	v_cmp_gt_u32_e64 s[6:7], s54, v10
	v_cmp_lt_u32_e32 vcc, s53, v10
	s_nop 0
	v_cndmask_b32_e64 v7, v7, v10, s[6:7]
	v_lshlrev_b64 v[10:11], 10, v[20:21]
	v_cndmask_b32_e32 v0, 0, v16, vcc
	v_lshl_add_u64 v[10:11], s[24:25], 0, v[10:11]
	v_lshl_add_u64 v[10:11], v[10:11], 0, v[0:1]
	v_cndmask_b32_e32 v0, 0, v17, vcc
	v_lshl_add_u64 v[8:9], v[8:9], 0, v[0:1]
	v_lshlrev_b32_sdwa v0, v18, v7 dst_sel:DWORD dst_unused:UNUSED_PAD src0_sel:DWORD src1_sel:WORD_0
	v_lshl_add_u64 v[8:9], v[8:9], 0, v[0:1]
	v_lshl_add_u64 v[20:21], v[8:9], 0, s[12:13]
	v_lshl_add_u64 v[8:9], v[8:9], 0, s[14:15]
	v_cmp_gt_u16_e32 vcc, 48, v7
	s_nop 1
	v_cndmask_b32_e32 v9, v21, v9, vcc
	v_cndmask_b32_e32 v8, v20, v8, vcc
	global_load_dword v102, v[8:9], off
	v_lshl_add_u64 v[116:117], v[10:11], 0, v[0:1]
	s_waitcnt vmcnt(6)
	global_store_dword v[104:105], v96, off offset:64
	s_waitcnt vmcnt(6)
	global_store_dword v[106:107], v97, off offset:64
	s_waitcnt vmcnt(6)
	global_store_dword v[108:109], v98, off offset:64
	s_waitcnt vmcnt(6)
	global_store_dword v[110:111], v99, off offset:64
	s_waitcnt vmcnt(6)
	global_store_dword v[112:113], v100, off offset:64
	s_waitcnt vmcnt(6)
	global_store_dword v[114:115], v101, off offset:64
	s_waitcnt vmcnt(6)
	global_store_dword v[116:117], v102, off offset:64
	s_or_b64 exec, exec, s[16:17]
	s_and_saveexec_b64 s[6:7], s[4:5]
	s_cbranch_execz .LBB0_764
	v_add_u32_e32 v0, s57, v12
	v_mov_b64_e32 v[6:7], s[34:35]
	v_mad_i64_i32 v[6:7], s[16:17], v0, s28, v[6:7]
	v_lshl_add_u64 v[8:9], v[6:7], 0, v[4:5]
	v_add_co_u32_e32 v8, vcc, 0x2000, v8
	v_mad_i64_i32 v[6:7], s[16:17], v0, s56, v[6:7]
	s_nop 0
	v_addc_co_u32_e32 v9, vcc, 0, v9, vcc
	global_load_dword v8, v[8:9], off offset:2592
	v_lshl_add_u64 v[6:7], v[6:7], 0, v[4:5]
	v_add_co_u32_e32 v6, vcc, 0x1de00000, v6
	s_nop 1
	v_addc_co_u32_e32 v7, vcc, 0, v7, vcc
	s_waitcnt vmcnt(0)
	global_store_dword v[6:7], v8, off offset:32
	s_branch .LBB0_764
